# S5 scan token loops: input-tile LDS reads hoisted ahead with pool-renamed destinations, counted lgkmcnt
# baseline (speedup 1.0000x reference)
; #define LAS __attribute__((address_space(3)))
; DI float lo16(unsigned u) { return __uint_as_float(u << 16); }
; DI float hi16(unsigned u) { return __uint_as_float(u & 0xffff0000u); }
; DI void lds_wait() { asm volatile("s_waitcnt lgkmcnt(0)" ::: "memory"); }
; template <bool PASSB>
; DI void s5_pass(const int tid, LAS unsigned char* lds, const P& p, int G, int c0) {
;     ...
;         for (int tile = 0; tile < 16; ++tile) {
;             if (lane < 32) { const int tk = lane >> 1, hf = lane & 1;
;                 const u32x4 raw = *(const u32x4*)(us5 + (tokbase + tile * 16 + tk) * 256 + g * 16 + hf * 8);
;                 LAS float* d = ubuf + tk * 16 + hf * 8;
;                 *(LAS f32x4*)d = (f32x4){lo16(raw.x), hi16(raw.x), lo16(raw.y), hi16(raw.y)}; *(LAS f32x4*)(d + 4) = (f32x4){lo16(raw.z), hi16(raw.z), lo16(raw.w), hi16(raw.w)}; }
;             lds_wait();
; #pragma unroll 8
;             for (int t = 0; t < 16; ++t) {
;                 float bur = 0.f, bui = 0.f;
; #pragma unroll
;                 for (int k = 0; k < 4; ++k) { const f32x4 u = *(const LAS f32x4*)(ubuf + t * 16 + k * 4);
; #pragma unroll
;                     for (int e = 0; e < 4; ++e) { bur += bre[4 * k + e] * u[e]; bui += bim[4 * k + e] * u[e]; } }
;                 const float nr = are * hre - aim * him + bur, ni = are * him + aim * hre + bui; hre = nr; him = ni;
;                 if (PASSB) { hbuf[t * 136 + lane] = f2bf(hre); hbuf[t * 136 + 64 + lane] = f2bf(-him); }
.LBB0_576:
	v_add_u32_e32 v33, s0, v77
	ds_read_b128 v[114:117], v33
	ds_read_b128 v[118:121], v33 offset:16
	ds_read_b128 v[122:125], v33 offset:32
	ds_read_b128 v[126:129], v33 offset:48
	ds_read_b128 v[130:133], v33 offset:64
	ds_read_b128 v[134:137], v33 offset:80
	ds_read_b128 v[138:141], v33 offset:96
	ds_read_b128 v[142:145], v33 offset:112
	ds_read_b128 v[150:153], v33 offset:128
	v_add_u32_e32 v91, v77, v32
	s_waitcnt lgkmcnt(8)
	v_pk_fma_f32 v[34:35], v[12:13], v[114:115], 0 op_sel_hi:[1,0,0]
	v_add_u32_e32 v32, 0x880, v32
	v_pk_fma_f32 v[34:35], v[38:39], v[114:115], v[34:35] op_sel:[0,1,0]
	ds_read_b128 v[154:157], v33 offset:144
	v_mov_b32_e32 v92, v117
	v_pk_fma_f32 v[34:35], v[14:15], v[116:117], v[34:35] op_sel_hi:[1,0,1]
	s_waitcnt lgkmcnt(8)
	v_mov_b32_e32 v94, v121
	v_pk_fma_f32 v[34:35], v[72:73], v[92:93], v[34:35] op_sel_hi:[1,0,1]
	v_pk_mul_f32 v[92:93], v[36:37], v[74:75] op_sel:[0,1]
	v_pk_fma_f32 v[34:35], v[8:9], v[118:119], v[34:35] op_sel_hi:[1,0,1]
	s_nop 0
	v_pk_fma_f32 v[34:35], v[70:71], v[118:119], v[34:35] op_sel:[0,1,0]
	ds_read_b128 v[158:161], v33 offset:160
	v_pk_fma_f32 v[34:35], v[10:11], v[120:121], v[34:35] op_sel_hi:[1,0,1]
	s_nop 0
	v_pk_fma_f32 v[34:35], v[40:41], v[94:95], v[34:35] op_sel_hi:[1,0,1]
	s_waitcnt lgkmcnt(8)
	v_mov_b32_e32 v94, v125
	v_pk_fma_f32 v[34:35], v[4:5], v[122:123], v[34:35] op_sel_hi:[1,0,1]
	s_nop 0
	v_pk_fma_f32 v[34:35], v[42:43], v[122:123], v[34:35] op_sel:[0,1,0]
	ds_read_b128 v[162:165], v33 offset:176
	v_pk_fma_f32 v[34:35], v[6:7], v[124:125], v[34:35] op_sel_hi:[1,0,1]
	s_nop 0
	v_pk_fma_f32 v[34:35], v[44:45], v[94:95], v[34:35] op_sel_hi:[1,0,1]
	s_waitcnt lgkmcnt(8)
	v_mov_b32_e32 v94, v129
	v_pk_fma_f32 v[34:35], v[0:1], v[126:127], v[34:35] op_sel_hi:[1,0,1]
	s_nop 0
	v_pk_fma_f32 v[34:35], v[46:47], v[126:127], v[34:35] op_sel:[0,1,0]
	s_nop 0
	v_pk_fma_f32 v[34:35], v[2:3], v[128:129], v[34:35] op_sel_hi:[1,0,1]
	s_nop 0
	v_pk_fma_f32 v[34:35], v[68:69], v[94:95], v[34:35] op_sel_hi:[1,0,1]
	v_pk_fma_f32 v[94:95], v[60:61], v[74:75], v[92:93] neg_lo:[0,0,1] neg_hi:[0,0,1]
	v_pk_fma_f32 v[74:75], v[60:61], v[74:75], v[92:93] op_sel_hi:[1,0,1]
	s_nop 0
	v_mov_b32_e32 v95, v75
	v_pk_add_f32 v[34:35], v[94:95], v[34:35]
	s_nop 0
	v_cvt_pk_bf16_f32 v74, v34, s0
	ds_write_b16 v91, v74
	ds_read_b128 v[114:117], v33 offset:192
	v_cvt_pk_bf16_f32 v74, -v35, s0
	ds_write_b16 v91, v74 offset:128
	s_waitcnt lgkmcnt(10)
	v_pk_fma_f32 v[74:75], v[12:13], v[130:131], 0 op_sel_hi:[1,0,0]
	s_nop 0
	v_pk_fma_f32 v[74:75], v[38:39], v[130:131], v[74:75] op_sel:[0,1,0]
	ds_read_b128 v[118:121], v33 offset:208
	v_mov_b32_e32 v92, v133
	v_pk_fma_f32 v[74:75], v[14:15], v[132:133], v[74:75] op_sel_hi:[1,0,1]
	s_waitcnt lgkmcnt(10)
	v_mov_b32_e32 v94, v137
	v_pk_fma_f32 v[74:75], v[72:73], v[92:93], v[74:75] op_sel_hi:[1,0,1]
	v_pk_mul_f32 v[92:93], v[36:37], v[34:35] op_sel:[0,1]
	v_pk_fma_f32 v[74:75], v[8:9], v[134:135], v[74:75] op_sel_hi:[1,0,1]
	s_nop 0
	v_pk_fma_f32 v[74:75], v[70:71], v[134:135], v[74:75] op_sel:[0,1,0]
	ds_read_b128 v[122:125], v33 offset:224
	v_pk_fma_f32 v[74:75], v[10:11], v[136:137], v[74:75] op_sel_hi:[1,0,1]
	s_nop 0
	v_pk_fma_f32 v[74:75], v[40:41], v[94:95], v[74:75] op_sel_hi:[1,0,1]
	s_waitcnt lgkmcnt(10)
	v_mov_b32_e32 v94, v141
	v_pk_fma_f32 v[74:75], v[4:5], v[138:139], v[74:75] op_sel_hi:[1,0,1]
	s_nop 0
	v_pk_fma_f32 v[74:75], v[42:43], v[138:139], v[74:75] op_sel:[0,1,0]
	ds_read_b128 v[126:129], v33 offset:240
	v_pk_fma_f32 v[74:75], v[6:7], v[140:141], v[74:75] op_sel_hi:[1,0,1]
	s_nop 0
	v_pk_fma_f32 v[74:75], v[44:45], v[94:95], v[74:75] op_sel_hi:[1,0,1]
	s_waitcnt lgkmcnt(10)
	v_mov_b32_e32 v94, v145
	v_pk_fma_f32 v[74:75], v[0:1], v[142:143], v[74:75] op_sel_hi:[1,0,1]
	s_nop 0
	v_pk_fma_f32 v[74:75], v[46:47], v[142:143], v[74:75] op_sel:[0,1,0]
	s_nop 0
	v_pk_fma_f32 v[74:75], v[2:3], v[144:145], v[74:75] op_sel_hi:[1,0,1]
	s_nop 0
	v_pk_fma_f32 v[74:75], v[68:69], v[94:95], v[74:75] op_sel_hi:[1,0,1]
	v_pk_fma_f32 v[94:95], v[60:61], v[34:35], v[92:93] neg_lo:[0,0,1] neg_hi:[0,0,1]
	v_pk_fma_f32 v[34:35], v[60:61], v[34:35], v[92:93] op_sel_hi:[1,0,1]
	s_nop 0
	v_mov_b32_e32 v95, v35
	v_pk_add_f32 v[34:35], v[94:95], v[74:75]
	s_nop 0
	v_cvt_pk_bf16_f32 v74, v34, s0
	ds_write_b16 v91, v74 offset:272
	ds_read_b128 v[130:133], v33 offset:256
	v_cvt_pk_bf16_f32 v74, -v35, s0
	ds_write_b16 v91, v74 offset:400
	s_waitcnt lgkmcnt(12)
	v_pk_fma_f32 v[74:75], v[12:13], v[150:151], 0 op_sel_hi:[1,0,0]
	s_nop 0
	v_pk_fma_f32 v[74:75], v[38:39], v[150:151], v[74:75] op_sel:[0,1,0]
	ds_read_b128 v[134:137], v33 offset:272
	v_mov_b32_e32 v92, v153
	v_pk_fma_f32 v[74:75], v[14:15], v[152:153], v[74:75] op_sel_hi:[1,0,1]
	s_waitcnt lgkmcnt(12)
	v_mov_b32_e32 v94, v157
	v_pk_fma_f32 v[74:75], v[72:73], v[92:93], v[74:75] op_sel_hi:[1,0,1]
	v_pk_mul_f32 v[92:93], v[36:37], v[34:35] op_sel:[0,1]
	v_pk_fma_f32 v[74:75], v[8:9], v[154:155], v[74:75] op_sel_hi:[1,0,1]
	s_nop 0
	v_pk_fma_f32 v[74:75], v[70:71], v[154:155], v[74:75] op_sel:[0,1,0]
	ds_read_b128 v[138:141], v33 offset:288
	v_pk_fma_f32 v[74:75], v[10:11], v[156:157], v[74:75] op_sel_hi:[1,0,1]
	s_nop 0
	v_pk_fma_f32 v[74:75], v[40:41], v[94:95], v[74:75] op_sel_hi:[1,0,1]
	s_waitcnt lgkmcnt(12)
	v_mov_b32_e32 v94, v161
	v_pk_fma_f32 v[74:75], v[4:5], v[158:159], v[74:75] op_sel_hi:[1,0,1]
	s_nop 0
	v_pk_fma_f32 v[74:75], v[42:43], v[158:159], v[74:75] op_sel:[0,1,0]
	ds_read_b128 v[142:145], v33 offset:304
	v_pk_fma_f32 v[74:75], v[6:7], v[160:161], v[74:75] op_sel_hi:[1,0,1]
	s_nop 0
	v_pk_fma_f32 v[74:75], v[44:45], v[94:95], v[74:75] op_sel_hi:[1,0,1]
	s_waitcnt lgkmcnt(12)
; #define LAS __attribute__((address_space(3)))
; template <bool PASSB>
; DI void s5_pass(const int tid, LAS unsigned char* lds, const P& p, int G, int c0) {
;     ...
;             for (int t = 0; t < 16; ++t) {
;                 float bur = 0.f, bui = 0.f;
; #pragma unroll
;                 for (int k = 0; k < 4; ++k) { const f32x4 u = *(const LAS f32x4*)(ubuf + t * 16 + k * 4);
; #pragma unroll
;                     for (int e = 0; e < 4; ++e) { bur += bre[4 * k + e] * u[e]; bui += bim[4 * k + e] * u[e]; } }
;                 const float nr = are * hre - aim * him + bur, ni = are * him + aim * hre + bui; hre = nr; him = ni;
;                 if (PASSB) { hbuf[t * 136 + lane] = f2bf(hre); hbuf[t * 136 + 64 + lane] = f2bf(-him); }
	v_mov_b32_e32 v94, v165
	v_pk_fma_f32 v[74:75], v[0:1], v[162:163], v[74:75] op_sel_hi:[1,0,1]
	s_nop 0
	v_pk_fma_f32 v[74:75], v[46:47], v[162:163], v[74:75] op_sel:[0,1,0]
	s_nop 0
	v_pk_fma_f32 v[74:75], v[2:3], v[164:165], v[74:75] op_sel_hi:[1,0,1]
	s_nop 0
	v_pk_fma_f32 v[74:75], v[68:69], v[94:95], v[74:75] op_sel_hi:[1,0,1]
	v_pk_fma_f32 v[94:95], v[60:61], v[34:35], v[92:93] neg_lo:[0,0,1] neg_hi:[0,0,1]
	v_pk_fma_f32 v[34:35], v[60:61], v[34:35], v[92:93] op_sel_hi:[1,0,1]
	s_nop 0
	v_mov_b32_e32 v95, v35
	v_pk_add_f32 v[34:35], v[94:95], v[74:75]
	s_nop 0
	v_cvt_pk_bf16_f32 v74, v34, s0
	ds_write_b16 v91, v74 offset:544
	ds_read_b128 v[150:153], v33 offset:320
	v_cvt_pk_bf16_f32 v74, -v35, s0
	ds_write_b16 v91, v74 offset:672
	s_waitcnt lgkmcnt(13)
	v_pk_fma_f32 v[74:75], v[12:13], v[114:115], 0 op_sel_hi:[1,0,0]
	s_nop 0
	v_pk_fma_f32 v[74:75], v[38:39], v[114:115], v[74:75] op_sel:[0,1,0]
	ds_read_b128 v[154:157], v33 offset:336
	v_mov_b32_e32 v92, v117
	v_pk_fma_f32 v[74:75], v[14:15], v[116:117], v[74:75] op_sel_hi:[1,0,1]
	s_waitcnt lgkmcnt(12)
	v_mov_b32_e32 v94, v121
	v_pk_fma_f32 v[74:75], v[72:73], v[92:93], v[74:75] op_sel_hi:[1,0,1]
	v_pk_mul_f32 v[92:93], v[36:37], v[34:35] op_sel:[0,1]
	v_pk_fma_f32 v[74:75], v[8:9], v[118:119], v[74:75] op_sel_hi:[1,0,1]
	s_nop 0
	v_pk_fma_f32 v[74:75], v[70:71], v[118:119], v[74:75] op_sel:[0,1,0]
	ds_read_b128 v[158:161], v33 offset:352
	v_pk_fma_f32 v[74:75], v[10:11], v[120:121], v[74:75] op_sel_hi:[1,0,1]
	s_nop 0
	v_pk_fma_f32 v[74:75], v[40:41], v[94:95], v[74:75] op_sel_hi:[1,0,1]
	s_waitcnt lgkmcnt(12)
	v_mov_b32_e32 v94, v125
	v_pk_fma_f32 v[74:75], v[4:5], v[122:123], v[74:75] op_sel_hi:[1,0,1]
	s_nop 0
	v_pk_fma_f32 v[74:75], v[42:43], v[122:123], v[74:75] op_sel:[0,1,0]
	ds_read_b128 v[162:165], v33 offset:368
	v_pk_fma_f32 v[74:75], v[6:7], v[124:125], v[74:75] op_sel_hi:[1,0,1]
	s_nop 0
	v_pk_fma_f32 v[74:75], v[44:45], v[94:95], v[74:75] op_sel_hi:[1,0,1]
	s_waitcnt lgkmcnt(12)
	v_mov_b32_e32 v94, v129
	v_pk_fma_f32 v[74:75], v[0:1], v[126:127], v[74:75] op_sel_hi:[1,0,1]
	s_nop 0
	v_pk_fma_f32 v[74:75], v[46:47], v[126:127], v[74:75] op_sel:[0,1,0]
	s_nop 0
	v_pk_fma_f32 v[74:75], v[2:3], v[128:129], v[74:75] op_sel_hi:[1,0,1]
	s_nop 0
	v_pk_fma_f32 v[74:75], v[68:69], v[94:95], v[74:75] op_sel_hi:[1,0,1]
	v_pk_fma_f32 v[94:95], v[60:61], v[34:35], v[92:93] neg_lo:[0,0,1] neg_hi:[0,0,1]
	v_pk_fma_f32 v[34:35], v[60:61], v[34:35], v[92:93] op_sel_hi:[1,0,1]
	s_nop 0
	v_mov_b32_e32 v95, v35
	v_pk_add_f32 v[34:35], v[94:95], v[74:75]
	s_nop 0
	v_cvt_pk_bf16_f32 v74, v34, s0
	ds_write_b16 v91, v74 offset:816
	ds_read_b128 v[114:117], v33 offset:384
	v_cvt_pk_bf16_f32 v74, -v35, s0
	ds_write_b16 v91, v74 offset:944
	s_waitcnt lgkmcnt(13)
	v_pk_fma_f32 v[74:75], v[12:13], v[130:131], 0 op_sel_hi:[1,0,0]
	s_nop 0
	v_pk_fma_f32 v[74:75], v[38:39], v[130:131], v[74:75] op_sel:[0,1,0]
	ds_read_b128 v[118:121], v33 offset:400
	v_mov_b32_e32 v92, v133
	v_pk_fma_f32 v[74:75], v[14:15], v[132:133], v[74:75] op_sel_hi:[1,0,1]
	s_waitcnt lgkmcnt(12)
	v_mov_b32_e32 v94, v137
	v_pk_fma_f32 v[74:75], v[72:73], v[92:93], v[74:75] op_sel_hi:[1,0,1]
	v_pk_mul_f32 v[92:93], v[36:37], v[34:35] op_sel:[0,1]
	v_pk_fma_f32 v[74:75], v[8:9], v[134:135], v[74:75] op_sel_hi:[1,0,1]
	s_nop 0
	v_pk_fma_f32 v[74:75], v[70:71], v[134:135], v[74:75] op_sel:[0,1,0]
	ds_read_b128 v[122:125], v33 offset:416
	v_pk_fma_f32 v[74:75], v[10:11], v[136:137], v[74:75] op_sel_hi:[1,0,1]
	s_nop 0
	v_pk_fma_f32 v[74:75], v[40:41], v[94:95], v[74:75] op_sel_hi:[1,0,1]
	s_waitcnt lgkmcnt(12)
	v_mov_b32_e32 v94, v141
	v_pk_fma_f32 v[74:75], v[4:5], v[138:139], v[74:75] op_sel_hi:[1,0,1]
	s_nop 0
	v_pk_fma_f32 v[74:75], v[42:43], v[138:139], v[74:75] op_sel:[0,1,0]
	ds_read_b128 v[126:129], v33 offset:432
	v_pk_fma_f32 v[74:75], v[6:7], v[140:141], v[74:75] op_sel_hi:[1,0,1]
	s_nop 0
	v_pk_fma_f32 v[74:75], v[44:45], v[94:95], v[74:75] op_sel_hi:[1,0,1]
	s_waitcnt lgkmcnt(12)
	v_mov_b32_e32 v94, v145
	v_pk_fma_f32 v[74:75], v[0:1], v[142:143], v[74:75] op_sel_hi:[1,0,1]
	s_nop 0
	v_pk_fma_f32 v[74:75], v[46:47], v[142:143], v[74:75] op_sel:[0,1,0]
	s_nop 0
	v_pk_fma_f32 v[74:75], v[2:3], v[144:145], v[74:75] op_sel_hi:[1,0,1]
	s_nop 0
	v_pk_fma_f32 v[74:75], v[68:69], v[94:95], v[74:75] op_sel_hi:[1,0,1]
	v_pk_fma_f32 v[94:95], v[60:61], v[34:35], v[92:93] neg_lo:[0,0,1] neg_hi:[0,0,1]
	v_pk_fma_f32 v[34:35], v[60:61], v[34:35], v[92:93] op_sel_hi:[1,0,1]
	s_nop 0
	v_mov_b32_e32 v95, v35
	v_pk_add_f32 v[34:35], v[94:95], v[74:75]
	s_nop 0
	v_cvt_pk_bf16_f32 v74, v34, s0
	ds_write_b16 v91, v74 offset:1088
	ds_read_b128 v[130:133], v33 offset:448
	v_cvt_pk_bf16_f32 v74, -v35, s0
	ds_write_b16 v91, v74 offset:1216
	s_waitcnt lgkmcnt(13)
	v_pk_fma_f32 v[74:75], v[12:13], v[150:151], 0 op_sel_hi:[1,0,0]
	s_nop 0
	v_pk_fma_f32 v[74:75], v[38:39], v[150:151], v[74:75] op_sel:[0,1,0]
	ds_read_b128 v[134:137], v33 offset:464
	v_mov_b32_e32 v92, v153
	v_pk_fma_f32 v[74:75], v[14:15], v[152:153], v[74:75] op_sel_hi:[1,0,1]
	s_waitcnt lgkmcnt(12)
	v_mov_b32_e32 v94, v157
	v_pk_fma_f32 v[74:75], v[72:73], v[92:93], v[74:75] op_sel_hi:[1,0,1]
	v_pk_mul_f32 v[92:93], v[36:37], v[34:35] op_sel:[0,1]
	v_pk_fma_f32 v[74:75], v[8:9], v[154:155], v[74:75] op_sel_hi:[1,0,1]
	s_nop 0
	v_pk_fma_f32 v[74:75], v[70:71], v[154:155], v[74:75] op_sel:[0,1,0]
	ds_read_b128 v[138:141], v33 offset:480
	v_pk_fma_f32 v[74:75], v[10:11], v[156:157], v[74:75] op_sel_hi:[1,0,1]
	s_nop 0
	v_pk_fma_f32 v[74:75], v[40:41], v[94:95], v[74:75] op_sel_hi:[1,0,1]
	s_waitcnt lgkmcnt(12)
; #define LAS __attribute__((address_space(3)))
; template <bool PASSB>
; DI void s5_pass(const int tid, LAS unsigned char* lds, const P& p, int G, int c0) {
;     ...
;             for (int t = 0; t < 16; ++t) {
;                 float bur = 0.f, bui = 0.f;
; #pragma unroll
;                 for (int k = 0; k < 4; ++k) { const f32x4 u = *(const LAS f32x4*)(ubuf + t * 16 + k * 4);
; #pragma unroll
;                     for (int e = 0; e < 4; ++e) { bur += bre[4 * k + e] * u[e]; bui += bim[4 * k + e] * u[e]; } }
;                 const float nr = are * hre - aim * him + bur, ni = are * him + aim * hre + bui; hre = nr; him = ni;
;                 if (PASSB) { hbuf[t * 136 + lane] = f2bf(hre); hbuf[t * 136 + 64 + lane] = f2bf(-him); }
	v_mov_b32_e32 v94, v161
	v_pk_fma_f32 v[74:75], v[4:5], v[158:159], v[74:75] op_sel_hi:[1,0,1]
	s_nop 0
	v_pk_fma_f32 v[74:75], v[42:43], v[158:159], v[74:75] op_sel:[0,1,0]
	ds_read_b128 v[142:145], v33 offset:496
	v_pk_fma_f32 v[74:75], v[6:7], v[160:161], v[74:75] op_sel_hi:[1,0,1]
	s_nop 0
	v_pk_fma_f32 v[74:75], v[44:45], v[94:95], v[74:75] op_sel_hi:[1,0,1]
	s_waitcnt lgkmcnt(12)
	v_mov_b32_e32 v94, v165
	v_pk_fma_f32 v[74:75], v[0:1], v[162:163], v[74:75] op_sel_hi:[1,0,1]
	s_nop 0
	v_pk_fma_f32 v[74:75], v[46:47], v[162:163], v[74:75] op_sel:[0,1,0]
	s_nop 0
	v_pk_fma_f32 v[74:75], v[2:3], v[164:165], v[74:75] op_sel_hi:[1,0,1]
	s_nop 0
	v_pk_fma_f32 v[74:75], v[68:69], v[94:95], v[74:75] op_sel_hi:[1,0,1]
	v_pk_fma_f32 v[94:95], v[60:61], v[34:35], v[92:93] neg_lo:[0,0,1] neg_hi:[0,0,1]
	v_pk_fma_f32 v[34:35], v[60:61], v[34:35], v[92:93] op_sel_hi:[1,0,1]
	s_nop 0
	v_mov_b32_e32 v95, v35
	v_pk_add_f32 v[34:35], v[94:95], v[74:75]
	s_nop 0
	v_cvt_pk_bf16_f32 v74, v34, s0
	ds_write_b16 v91, v74 offset:1360
	v_cvt_pk_bf16_f32 v74, -v35, s0
	ds_write_b16 v91, v74 offset:1488
	s_waitcnt lgkmcnt(12)
	v_pk_fma_f32 v[74:75], v[12:13], v[114:115], 0 op_sel_hi:[1,0,0]
	s_nop 0
	v_pk_fma_f32 v[74:75], v[38:39], v[114:115], v[74:75] op_sel:[0,1,0]
	v_mov_b32_e32 v92, v117
	v_pk_fma_f32 v[74:75], v[14:15], v[116:117], v[74:75] op_sel_hi:[1,0,1]
	s_waitcnt lgkmcnt(10)
	v_mov_b32_e32 v94, v121
	v_pk_fma_f32 v[74:75], v[72:73], v[92:93], v[74:75] op_sel_hi:[1,0,1]
	v_pk_mul_f32 v[92:93], v[36:37], v[34:35] op_sel:[0,1]
	v_pk_fma_f32 v[74:75], v[8:9], v[118:119], v[74:75] op_sel_hi:[1,0,1]
	s_nop 0
	v_pk_fma_f32 v[74:75], v[70:71], v[118:119], v[74:75] op_sel:[0,1,0]
	s_nop 0
	v_pk_fma_f32 v[74:75], v[10:11], v[120:121], v[74:75] op_sel_hi:[1,0,1]
	s_nop 0
	v_pk_fma_f32 v[74:75], v[40:41], v[94:95], v[74:75] op_sel_hi:[1,0,1]
	s_waitcnt lgkmcnt(9)
	v_mov_b32_e32 v94, v125
	v_pk_fma_f32 v[74:75], v[4:5], v[122:123], v[74:75] op_sel_hi:[1,0,1]
	s_nop 0
	v_pk_fma_f32 v[74:75], v[42:43], v[122:123], v[74:75] op_sel:[0,1,0]
	s_nop 0
	v_pk_fma_f32 v[74:75], v[6:7], v[124:125], v[74:75] op_sel_hi:[1,0,1]
	s_nop 0
	v_pk_fma_f32 v[74:75], v[44:45], v[94:95], v[74:75] op_sel_hi:[1,0,1]
	s_waitcnt lgkmcnt(8)
	v_mov_b32_e32 v94, v129
	v_pk_fma_f32 v[74:75], v[0:1], v[126:127], v[74:75] op_sel_hi:[1,0,1]
	s_nop 0
	v_pk_fma_f32 v[74:75], v[46:47], v[126:127], v[74:75] op_sel:[0,1,0]
	s_nop 0
	v_pk_fma_f32 v[74:75], v[2:3], v[128:129], v[74:75] op_sel_hi:[1,0,1]
	s_nop 0
	v_pk_fma_f32 v[74:75], v[68:69], v[94:95], v[74:75] op_sel_hi:[1,0,1]
	v_pk_fma_f32 v[94:95], v[60:61], v[34:35], v[92:93] neg_lo:[0,0,1] neg_hi:[0,0,1]
	v_pk_fma_f32 v[34:35], v[60:61], v[34:35], v[92:93] op_sel_hi:[1,0,1]
	s_nop 0
	v_mov_b32_e32 v95, v35
	v_pk_add_f32 v[34:35], v[94:95], v[74:75]
	s_nop 0
	v_cvt_pk_bf16_f32 v74, v34, s0
	ds_write_b16 v91, v74 offset:1632
	v_cvt_pk_bf16_f32 v74, -v35, s0
	ds_write_b16 v91, v74 offset:1760
	s_waitcnt lgkmcnt(8)
	v_pk_fma_f32 v[74:75], v[12:13], v[130:131], 0 op_sel_hi:[1,0,0]
	s_nop 0
	v_pk_fma_f32 v[74:75], v[38:39], v[130:131], v[74:75] op_sel:[0,1,0]
	v_mov_b32_e32 v92, v133
	v_pk_fma_f32 v[74:75], v[14:15], v[132:133], v[74:75] op_sel_hi:[1,0,1]
	s_waitcnt lgkmcnt(6)
	v_mov_b32_e32 v94, v137
	v_pk_fma_f32 v[74:75], v[72:73], v[92:93], v[74:75] op_sel_hi:[1,0,1]
	v_pk_mul_f32 v[92:93], v[36:37], v[34:35] op_sel:[0,1]
	v_pk_fma_f32 v[74:75], v[8:9], v[134:135], v[74:75] op_sel_hi:[1,0,1]
	s_nop 0
	v_pk_fma_f32 v[74:75], v[70:71], v[134:135], v[74:75] op_sel:[0,1,0]
	s_nop 0
	v_pk_fma_f32 v[74:75], v[10:11], v[136:137], v[74:75] op_sel_hi:[1,0,1]
	s_nop 0
	v_pk_fma_f32 v[74:75], v[40:41], v[94:95], v[74:75] op_sel_hi:[1,0,1]
	s_waitcnt lgkmcnt(5)
	v_mov_b32_e32 v94, v141
	v_pk_fma_f32 v[74:75], v[4:5], v[138:139], v[74:75] op_sel_hi:[1,0,1]
	s_nop 0
	v_pk_fma_f32 v[74:75], v[42:43], v[138:139], v[74:75] op_sel:[0,1,0]
	s_nop 0
	v_pk_fma_f32 v[74:75], v[6:7], v[140:141], v[74:75] op_sel_hi:[1,0,1]
	s_nop 0
	v_pk_fma_f32 v[74:75], v[44:45], v[94:95], v[74:75] op_sel_hi:[1,0,1]
	s_waitcnt lgkmcnt(4)
	v_mov_b32_e32 v94, v145
	v_pk_fma_f32 v[74:75], v[0:1], v[142:143], v[74:75] op_sel_hi:[1,0,1]
	s_nop 0
	v_pk_fma_f32 v[74:75], v[46:47], v[142:143], v[74:75] op_sel:[0,1,0]
	s_nop 0
	v_pk_fma_f32 v[74:75], v[2:3], v[144:145], v[74:75] op_sel_hi:[1,0,1]
	s_nop 0
	v_pk_fma_f32 v[74:75], v[68:69], v[94:95], v[74:75] op_sel_hi:[1,0,1]
	v_pk_fma_f32 v[94:95], v[60:61], v[34:35], v[92:93] neg_lo:[0,0,1] neg_hi:[0,0,1]
	v_pk_fma_f32 v[34:35], v[60:61], v[34:35], v[92:93] op_sel_hi:[1,0,1]
	s_nop 0
	v_mov_b32_e32 v95, v35
	v_pk_add_f32 v[74:75], v[94:95], v[74:75]
	s_nop 0
	v_cvt_pk_bf16_f32 v33, v74, s0
	ds_write_b16 v91, v33 offset:1904
	v_cvt_pk_bf16_f32 v33, -v75, s0
	s_addk_i32 s0, 0x200
	s_cmpk_lg_i32 s0, 0x400
	ds_write_b16 v91, v33 offset:2032
	s_cbranch_scc1 .LBB0_576
; #define LAS __attribute__((address_space(3)))
; DI float gelu_tanh(float x) { float u = 0.7978845608028654f * (x + 0.044715f * x * x * x); float e = __expf(2.f * u); float th = 1.f - 2.f / (e + 1.f); return 0.5f * x * (1.f + th); }
; DI f32x4 mfma16(bf16x8 a, bf16x8 b, f32x4 c) { return __builtin_amdgcn_mfma_f32_16x16x32_bf16(a, b, c, 0, 0, 0); }
; DI void lds_wait() { asm volatile("s_waitcnt lgkmcnt(0)" ::: "memory"); }
; template <bool PASSB>
; DI void s5_pass(const int tid, LAS unsigned char* lds, const P& p, int G, int c0) {
;     ...
;             if (PASSB) {
;                 lds_wait();
;                 f32x4 acc = (f32x4){0.f, 0.f, 0.f, 0.f};
; #pragma unroll
;                 for (int ks = 0; ks < 4; ++ks) { const bf16x8 a = *(const LAS bf16x8*)(hbuf + fr * 136 + ks * 32 + fq * 8); acc = mfma16(a, cf[ks], acc); }
; #pragma unroll
;                 for (int j = 0; j < 4; ++j) { const int tk = fq * 4 + j; const float y = acc[j] + dsk * ubuf[tk * 16 + fr];
;                     zs5[(tokbase + tile * 16 + tk) * 256 + g * 16 + fr] = f2bf(gelu_tanh(y)); }
;             }
;             lds_wait();
;         }
;         if (!PASSB) { float* he = hend + (((size_t)(b * 16 + g) * 8 + seg) * 64 + lane) * 2; he[0] = hre; he[1] = him; }
	s_waitcnt lgkmcnt(0)
	v_add_u32_e32 v91, v80, v48
	ds_read_b128 v[32:35], v91 offset:1024
	ds_read_b128 v[92:95], v91 offset:1088
	s_lshl_b32 s0, s8, 4
	s_add_i32 s8, s8, 1
	s_cmp_eq_u32 s8, 16
	s_waitcnt vmcnt(4) lgkmcnt(1)
	v_mfma_f32_16x16x32_bf16 v[32:35], v[32:35], v[16:19], 0
	s_waitcnt vmcnt(3) lgkmcnt(0)
	v_mfma_f32_16x16x32_bf16 v[32:35], v[92:95], v[20:23], v[32:35]
	ds_read_b128 v[92:95], v91 offset:1152
	s_waitcnt vmcnt(2) lgkmcnt(0)
	v_mfma_f32_16x16x32_bf16 v[32:35], v[92:95], v[24:27], v[32:35]
	ds_read_b128 v[92:95], v91 offset:1216
	ds_read_b32 v91, v86
	s_waitcnt vmcnt(1) lgkmcnt(1)
	v_mfma_f32_16x16x32_bf16 v[32:35], v[92:95], v[28:31], v[32:35]
	s_waitcnt vmcnt(0) lgkmcnt(0)
	s_nop 6
	v_fma_f32 v32, v90, v91, v32
	v_mul_f32_e32 v91, 0x3d372713, v32
	v_mul_f32_e32 v91, v32, v91
	v_fma_f32 v91, v32, v91, v32
	v_mul_f32_e32 v91, 0x3f4c422a, v91
	v_add_f32_e32 v91, v91, v91
	v_mul_f32_e32 v91, 0x3fb8aa3b, v91
	v_exp_f32_e32 v91, v91
	v_mul_f32_e32 v32, 0.5, v32
	v_add_f32_e32 v91, 1.0, v91
	v_div_scale_f32 v92, s[10:11], v91, v91, 2.0
	v_rcp_f32_e32 v93, v92
	s_nop 0
	v_fma_f32 v94, -v92, v93, 1.0
	v_fmac_f32_e32 v93, v94, v93
	v_div_scale_f32 v94, vcc, 2.0, v91, 2.0
	v_mul_f32_e32 v95, v94, v93
	v_fma_f32 v96, -v92, v95, v94
	v_fmac_f32_e32 v95, v96, v93
	v_fma_f32 v92, -v92, v95, v94
	v_div_fmas_f32 v92, v92, v93, v95
	v_div_fixup_f32 v91, v92, v91, 2.0
	v_sub_f32_e32 v91, 1.0, v91
	v_add_f32_e32 v91, 1.0, v91
	v_or3_b32 v92, s0, v81, v62
	v_mov_b32_e32 v93, v63
	v_mul_f32_e32 v32, v32, v91
	v_lshlrev_b64 v[92:93], 9, v[92:93]
	v_cvt_pk_bf16_f32 v32, v32, s0
	v_lshl_add_u64 v[92:93], v[66:67], 0, v[92:93]
	global_store_short v[92:93], v32, off
	ds_read_b32 v32, v87
	s_waitcnt lgkmcnt(0)
	v_fma_f32 v32, v90, v32, v33
	v_mul_f32_e32 v33, 0x3d372713, v32
	v_mul_f32_e32 v33, v32, v33
	v_fma_f32 v33, v32, v33, v32
	v_mul_f32_e32 v33, 0x3f4c422a, v33
	v_add_f32_e32 v33, v33, v33
	v_mul_f32_e32 v33, 0x3fb8aa3b, v33
	v_exp_f32_e32 v33, v33
	v_mul_f32_e32 v32, 0.5, v32
	v_add_f32_e32 v33, 1.0, v33
	v_div_scale_f32 v91, s[10:11], v33, v33, 2.0
	v_rcp_f32_e32 v92, v91
	s_nop 0
	v_fma_f32 v93, -v91, v92, 1.0
	v_fmac_f32_e32 v92, v93, v92
	v_div_scale_f32 v93, vcc, 2.0, v33, 2.0
	v_mul_f32_e32 v94, v93, v92
	v_fma_f32 v95, -v91, v94, v93
	v_fmac_f32_e32 v94, v95, v92
	v_fma_f32 v91, -v91, v94, v93
	v_div_fmas_f32 v91, v91, v92, v94
	v_div_fixup_f32 v33, v91, v33, 2.0
	v_sub_f32_e32 v33, 1.0, v33
	v_add_f32_e32 v33, 1.0, v33
	v_mul_f32_e32 v32, v32, v33
	v_cvt_pk_bf16_f32 v91, v32, s0
	v_or3_b32 v32, s0, v82, v62
	v_mov_b32_e32 v33, v63
	v_lshlrev_b64 v[32:33], 9, v[32:33]
	v_lshl_add_u64 v[32:33], v[66:67], 0, v[32:33]
	global_store_short v[32:33], v91, off
	ds_read_b32 v32, v88
	s_waitcnt lgkmcnt(0)
	v_fma_f32 v32, v90, v32, v34
	v_mul_f32_e32 v33, 0x3d372713, v32
	v_mul_f32_e32 v33, v32, v33
	v_fma_f32 v33, v32, v33, v32
	v_mul_f32_e32 v33, 0x3f4c422a, v33
	v_add_f32_e32 v33, v33, v33
	v_mul_f32_e32 v33, 0x3fb8aa3b, v33
	v_exp_f32_e32 v33, v33
	v_mul_f32_e32 v32, 0.5, v32
	v_add_f32_e32 v33, 1.0, v33
	v_div_scale_f32 v34, s[10:11], v33, v33, 2.0
	v_rcp_f32_e32 v91, v34
	s_nop 0
	v_fma_f32 v92, -v34, v91, 1.0
	v_fmac_f32_e32 v91, v92, v91
	v_div_scale_f32 v92, vcc, 2.0, v33, 2.0
	v_mul_f32_e32 v93, v92, v91
	v_fma_f32 v94, -v34, v93, v92
	v_fmac_f32_e32 v93, v94, v91
	v_fma_f32 v34, -v34, v93, v92
	v_div_fmas_f32 v34, v34, v91, v93
	v_div_fixup_f32 v33, v34, v33, 2.0
	v_sub_f32_e32 v33, 1.0, v33
	v_add_f32_e32 v33, 1.0, v33
	v_mul_f32_e32 v32, v32, v33
	v_cvt_pk_bf16_f32 v34, v32, s0
	v_or3_b32 v32, s0, v83, v62
	v_mov_b32_e32 v33, v63
	v_lshlrev_b64 v[32:33], 9, v[32:33]
	v_lshl_add_u64 v[32:33], v[66:67], 0, v[32:33]
	global_store_short v[32:33], v34, off
	ds_read_b32 v32, v89
	s_waitcnt lgkmcnt(0)
	v_fmac_f32_e32 v35, v90, v32
	v_mul_f32_e32 v32, 0x3d372713, v35
	v_mul_f32_e32 v32, v35, v32
	v_fma_f32 v32, v35, v32, v35
	v_mul_f32_e32 v32, 0x3f4c422a, v32
	v_add_f32_e32 v32, v32, v32
	v_mul_f32_e32 v32, 0x3fb8aa3b, v32
	v_exp_f32_e32 v32, v32
	s_nop 0
	v_add_f32_e32 v32, 1.0, v32
	v_div_scale_f32 v33, s[10:11], v32, v32, 2.0
	v_rcp_f32_e32 v34, v33
	s_nop 0
	v_fma_f32 v91, -v33, v34, 1.0
	v_fmac_f32_e32 v34, v91, v34
	v_div_scale_f32 v91, vcc, 2.0, v32, 2.0
	v_mul_f32_e32 v92, v91, v34
	v_fma_f32 v93, -v33, v92, v91
	v_fmac_f32_e32 v92, v93, v34
	v_fma_f32 v33, -v33, v92, v91
	v_div_fmas_f32 v33, v33, v34, v92
	v_div_fixup_f32 v32, v33, v32, 2.0
	v_sub_f32_e32 v32, 1.0, v32
	v_mul_f32_e32 v33, 0.5, v35
	v_add_f32_e32 v32, 1.0, v32
	v_mul_f32_e32 v32, v33, v32
	v_cvt_pk_bf16_f32 v34, v32, s0
	v_or3_b32 v32, s0, v84, v62
	v_mov_b32_e32 v33, v63
	v_lshlrev_b64 v[32:33], 9, v[32:33]
	v_lshl_add_u64 v[32:33], v[66:67], 0, v[32:33]
	global_store_short v[32:33], v34, off
	s_waitcnt lgkmcnt(0)
	s_cbranch_scc0 .LBB0_573
	v_readlane_b32 s0, v253, 16
	s_add_i32 s12, s12, s0
	s_cmpk_gt_i32 s12, 0x1ff
	v_readlane_b32 s1, v253, 17
	s_cbranch_scc0 .LBB0_568
	s_mov_b32 s64, s13
	s_mov_b32 s67, s26
	s_mov_b32 s66, s28

; #define LAS __attribute__((address_space(3)))
; DI float lo16(unsigned u) { return __uint_as_float(u << 16); }
; DI float hi16(unsigned u) { return __uint_as_float(u & 0xffff0000u); }
; DI void lds_wait() { asm volatile("s_waitcnt lgkmcnt(0)" ::: "memory"); }
; template <bool PASSB>
; DI void s5_pass(const int tid, LAS unsigned char* lds, const P& p, int G, int c0) {
;     ...
;         for (int tile = 0; tile < 16; ++tile) {
;             if (lane < 32) { const int tk = lane >> 1, hf = lane & 1;
;                 const u32x4 raw = *(const u32x4*)(us5 + (tokbase + tile * 16 + tk) * 256 + g * 16 + hf * 8);
;                 LAS float* d = ubuf + tk * 16 + hf * 8;
;                 *(LAS f32x4*)d = (f32x4){lo16(raw.x), hi16(raw.x), lo16(raw.y), hi16(raw.y)}; *(LAS f32x4*)(d + 4) = (f32x4){lo16(raw.z), hi16(raw.z), lo16(raw.w), hi16(raw.w)}; }
;             lds_wait();
; #pragma unroll 8
;             for (int t = 0; t < 16; ++t) {
;                 float bur = 0.f, bui = 0.f;
; #pragma unroll
;                 for (int k = 0; k < 4; ++k) { const f32x4 u = *(const LAS f32x4*)(ubuf + t * 16 + k * 4);
; #pragma unroll
;                     for (int e = 0; e < 4; ++e) { bur += bre[4 * k + e] * u[e]; bui += bim[4 * k + e] * u[e]; } }
;                 const float nr = are * hre - aim * him + bur, ni = are * him + aim * hre + bui; hre = nr; him = ni;
.LBB0_588:
	v_add_u32_e32 v25, s0, v51
	ds_read_b128 v[72:75], v25
	ds_read_b128 v[76:79], v25 offset:16
	ds_read_b128 v[80:83], v25 offset:32
	ds_read_b128 v[84:87], v25 offset:48
	ds_read_b128 v[88:91], v25 offset:64
	ds_read_b128 v[92:95], v25 offset:80
	ds_read_b128 v[96:99], v25 offset:96
	ds_read_b128 v[100:103], v25 offset:112
	ds_read_b128 v[104:107], v25 offset:128
	ds_read_b128 v[108:111], v25 offset:144
	s_addk_i32 s0, 0x200
	s_waitcnt lgkmcnt(9)
	v_pk_fma_f32 v[70:71], v[12:13], v[72:73], 0 op_sel_hi:[1,0,0]
	s_cmpk_lg_i32 s0, 0x400
	v_pk_fma_f32 v[54:55], v[44:45], v[72:73], v[70:71] op_sel:[0,1,0]
	ds_read_b128 v[112:115], v25 offset:160
	v_pk_fma_f32 v[54:55], v[14:15], v[74:75], v[54:55] op_sel_hi:[1,0,1]
	v_mov_b32_e32 v56, v75
	v_pk_fma_f32 v[54:55], v[42:43], v[56:57], v[54:55] op_sel_hi:[1,0,1]
	v_mov_b32_e32 v56, v49
	s_waitcnt lgkmcnt(9)
	v_pk_fma_f32 v[54:55], v[8:9], v[76:77], v[54:55] op_sel_hi:[1,0,1]
	ds_read_b128 v[116:119], v25 offset:176
	v_pk_mul_f32 v[56:57], v[46:47], v[56:57] op_sel_hi:[1,0]
	v_pk_fma_f32 v[54:55], v[40:41], v[76:77], v[54:55] op_sel:[0,1,0]
	v_mov_b32_e32 v58, v79
	v_pk_fma_f32 v[54:55], v[10:11], v[78:79], v[54:55] op_sel_hi:[1,0,1]
	s_nop 0
	v_pk_fma_f32 v[54:55], v[38:39], v[58:59], v[54:55] op_sel_hi:[1,0,1]
	s_waitcnt lgkmcnt(9)
	v_mov_b32_e32 v58, v83
	v_pk_fma_f32 v[54:55], v[4:5], v[80:81], v[54:55] op_sel_hi:[1,0,1]
	s_nop 0
	v_pk_fma_f32 v[54:55], v[36:37], v[80:81], v[54:55] op_sel:[0,1,0]
	s_nop 0
	v_pk_fma_f32 v[54:55], v[6:7], v[82:83], v[54:55] op_sel_hi:[1,0,1]
	s_nop 0
	v_pk_fma_f32 v[54:55], v[34:35], v[58:59], v[54:55] op_sel_hi:[1,0,1]
	ds_read_b128 v[72:75], v25 offset:192
	s_waitcnt lgkmcnt(9)
	v_mov_b32_e32 v58, v87
	v_pk_fma_f32 v[54:55], v[0:1], v[84:85], v[54:55] op_sel_hi:[1,0,1]
	s_nop 0
	v_pk_fma_f32 v[54:55], v[32:33], v[84:85], v[54:55] op_sel:[0,1,0]
	s_nop 0
	v_pk_fma_f32 v[54:55], v[2:3], v[86:87], v[54:55] op_sel_hi:[1,0,1]
	s_nop 0
	v_pk_fma_f32 v[54:55], v[30:31], v[58:59], v[54:55] op_sel_hi:[1,0,1]
	ds_read_b128 v[76:79], v25 offset:208
	v_pk_fma_f32 v[58:59], v[22:23], v[48:49], v[56:57] neg_lo:[0,0,1] neg_hi:[0,0,1]
	v_pk_fma_f32 v[48:49], v[22:23], v[48:49], v[56:57] op_sel_hi:[1,0,1]
	s_nop 0
	v_mov_b32_e32 v59, v49
	v_pk_add_f32 v[48:49], v[58:59], v[54:55]
	s_nop 0
	v_pk_mul_f32 v[66:67], v[46:47], v[48:49] op_sel:[0,1]
	ds_read_b128 v[80:83], v25 offset:224
	s_waitcnt lgkmcnt(10)
	v_pk_fma_f32 v[62:63], v[12:13], v[88:89], 0 op_sel_hi:[1,0,0]
	s_nop 0
	v_pk_fma_f32 v[54:55], v[44:45], v[88:89], v[62:63] op_sel:[0,1,0]
	s_nop 0
	v_pk_fma_f32 v[54:55], v[14:15], v[90:91], v[54:55] op_sel_hi:[1,0,1]
	v_mov_b32_e32 v56, v91
	v_pk_fma_f32 v[54:55], v[42:43], v[56:57], v[54:55] op_sel_hi:[1,0,1]
	ds_read_b128 v[84:87], v25 offset:240
	s_waitcnt lgkmcnt(10)
	v_pk_fma_f32 v[54:55], v[8:9], v[92:93], v[54:55] op_sel_hi:[1,0,1]
	s_nop 0
	v_pk_fma_f32 v[58:59], v[40:41], v[92:93], v[54:55] op_sel:[0,1,0]
	s_nop 0
	v_pk_fma_f32 v[58:59], v[10:11], v[94:95], v[58:59] op_sel_hi:[1,0,1]
	v_mov_b32_e32 v60, v95
	v_pk_fma_f32 v[58:59], v[38:39], v[60:61], v[58:59] op_sel_hi:[1,0,1]
	s_waitcnt lgkmcnt(9)
	v_pk_fma_f32 v[58:59], v[4:5], v[96:97], v[58:59] op_sel_hi:[1,0,1]
	s_nop 0
	v_pk_fma_f32 v[54:55], v[36:37], v[96:97], v[58:59] op_sel:[0,1,0]
	s_nop 0
	v_pk_fma_f32 v[54:55], v[6:7], v[98:99], v[54:55] op_sel_hi:[1,0,1]
	v_mov_b32_e32 v56, v99
	v_pk_fma_f32 v[54:55], v[34:35], v[56:57], v[54:55] op_sel_hi:[1,0,1]
	ds_read_b128 v[88:91], v25 offset:256
	s_waitcnt lgkmcnt(9)
	v_mov_b32_e32 v56, v103
	v_pk_fma_f32 v[54:55], v[0:1], v[100:101], v[54:55] op_sel_hi:[1,0,1]
	s_nop 0
	v_pk_fma_f32 v[54:55], v[32:33], v[100:101], v[54:55] op_sel:[0,1,0]
	s_nop 0
	v_pk_fma_f32 v[54:55], v[2:3], v[102:103], v[54:55] op_sel_hi:[1,0,1]
	s_nop 0
	v_pk_fma_f32 v[54:55], v[30:31], v[56:57], v[54:55] op_sel_hi:[1,0,1]
	ds_read_b128 v[92:95], v25 offset:272
	v_pk_fma_f32 v[56:57], v[22:23], v[48:49], v[66:67] neg_lo:[0,0,1] neg_hi:[0,0,1]
	v_pk_fma_f32 v[48:49], v[22:23], v[48:49], v[66:67] op_sel_hi:[1,0,1]
	s_nop 0
	v_mov_b32_e32 v57, v49
	v_pk_add_f32 v[48:49], v[56:57], v[54:55]
	s_nop 0
	v_pk_mul_f32 v[66:67], v[46:47], v[48:49] op_sel:[0,1]
	ds_read_b128 v[96:99], v25 offset:288
	s_waitcnt lgkmcnt(10)
	v_pk_fma_f32 v[62:63], v[12:13], v[104:105], 0 op_sel_hi:[1,0,0]
	s_nop 0
	v_pk_fma_f32 v[54:55], v[44:45], v[104:105], v[62:63] op_sel:[0,1,0]
	s_nop 0
	v_pk_fma_f32 v[54:55], v[14:15], v[106:107], v[54:55] op_sel_hi:[1,0,1]
	v_mov_b32_e32 v56, v107
	v_pk_fma_f32 v[54:55], v[42:43], v[56:57], v[54:55] op_sel_hi:[1,0,1]
	ds_read_b128 v[100:103], v25 offset:304
	s_waitcnt lgkmcnt(10)
	v_pk_fma_f32 v[54:55], v[8:9], v[108:109], v[54:55] op_sel_hi:[1,0,1]
	s_nop 0
	v_pk_fma_f32 v[58:59], v[40:41], v[108:109], v[54:55] op_sel:[0,1,0]
	s_nop 0
	v_pk_fma_f32 v[58:59], v[10:11], v[110:111], v[58:59] op_sel_hi:[1,0,1]
	v_mov_b32_e32 v60, v111
	v_pk_fma_f32 v[58:59], v[38:39], v[60:61], v[58:59] op_sel_hi:[1,0,1]
	s_waitcnt lgkmcnt(9)
	v_pk_fma_f32 v[58:59], v[4:5], v[112:113], v[58:59] op_sel_hi:[1,0,1]
	s_nop 0
	v_pk_fma_f32 v[54:55], v[36:37], v[112:113], v[58:59] op_sel:[0,1,0]
	s_nop 0
	v_pk_fma_f32 v[54:55], v[6:7], v[114:115], v[54:55] op_sel_hi:[1,0,1]
	v_mov_b32_e32 v56, v115
	v_pk_fma_f32 v[54:55], v[34:35], v[56:57], v[54:55] op_sel_hi:[1,0,1]
	ds_read_b128 v[104:107], v25 offset:320
	s_waitcnt lgkmcnt(9)
; #define LAS __attribute__((address_space(3)))
; template <bool PASSB>
; DI void s5_pass(const int tid, LAS unsigned char* lds, const P& p, int G, int c0) {
;     ...
;             for (int t = 0; t < 16; ++t) {
;                 float bur = 0.f, bui = 0.f;
; #pragma unroll
;                 for (int k = 0; k < 4; ++k) { const f32x4 u = *(const LAS f32x4*)(ubuf + t * 16 + k * 4);
; #pragma unroll
;                     for (int e = 0; e < 4; ++e) { bur += bre[4 * k + e] * u[e]; bui += bim[4 * k + e] * u[e]; } }
;                 const float nr = are * hre - aim * him + bur, ni = are * him + aim * hre + bui; hre = nr; him = ni;
	v_mov_b32_e32 v56, v119
	v_pk_fma_f32 v[54:55], v[0:1], v[116:117], v[54:55] op_sel_hi:[1,0,1]
	s_nop 0
	v_pk_fma_f32 v[54:55], v[32:33], v[116:117], v[54:55] op_sel:[0,1,0]
	s_nop 0
	v_pk_fma_f32 v[54:55], v[2:3], v[118:119], v[54:55] op_sel_hi:[1,0,1]
	s_nop 0
	v_pk_fma_f32 v[54:55], v[30:31], v[56:57], v[54:55] op_sel_hi:[1,0,1]
	ds_read_b128 v[108:111], v25 offset:336
	v_pk_fma_f32 v[56:57], v[22:23], v[48:49], v[66:67] neg_lo:[0,0,1] neg_hi:[0,0,1]
	v_pk_fma_f32 v[48:49], v[22:23], v[48:49], v[66:67] op_sel_hi:[1,0,1]
	s_nop 0
	v_mov_b32_e32 v57, v49
	v_pk_add_f32 v[48:49], v[56:57], v[54:55]
	s_nop 0
	v_pk_mul_f32 v[66:67], v[46:47], v[48:49] op_sel:[0,1]
	ds_read_b128 v[112:115], v25 offset:352
	s_waitcnt lgkmcnt(10)
	v_pk_fma_f32 v[62:63], v[12:13], v[72:73], 0 op_sel_hi:[1,0,0]
	s_nop 0
	v_pk_fma_f32 v[54:55], v[44:45], v[72:73], v[62:63] op_sel:[0,1,0]
	s_nop 0
	v_pk_fma_f32 v[54:55], v[14:15], v[74:75], v[54:55] op_sel_hi:[1,0,1]
	v_mov_b32_e32 v56, v75
	v_pk_fma_f32 v[54:55], v[42:43], v[56:57], v[54:55] op_sel_hi:[1,0,1]
	ds_read_b128 v[116:119], v25 offset:368
	s_waitcnt lgkmcnt(10)
	v_pk_fma_f32 v[54:55], v[8:9], v[76:77], v[54:55] op_sel_hi:[1,0,1]
	s_nop 0
	v_pk_fma_f32 v[58:59], v[40:41], v[76:77], v[54:55] op_sel:[0,1,0]
	s_nop 0
	v_pk_fma_f32 v[58:59], v[10:11], v[78:79], v[58:59] op_sel_hi:[1,0,1]
	v_mov_b32_e32 v60, v79
	v_pk_fma_f32 v[58:59], v[38:39], v[60:61], v[58:59] op_sel_hi:[1,0,1]
	s_waitcnt lgkmcnt(9)
	v_pk_fma_f32 v[58:59], v[4:5], v[80:81], v[58:59] op_sel_hi:[1,0,1]
	s_nop 0
	v_pk_fma_f32 v[54:55], v[36:37], v[80:81], v[58:59] op_sel:[0,1,0]
	s_nop 0
	v_pk_fma_f32 v[54:55], v[6:7], v[82:83], v[54:55] op_sel_hi:[1,0,1]
	v_mov_b32_e32 v56, v83
	v_pk_fma_f32 v[54:55], v[34:35], v[56:57], v[54:55] op_sel_hi:[1,0,1]
	ds_read_b128 v[72:75], v25 offset:384
	s_waitcnt lgkmcnt(9)
	v_mov_b32_e32 v56, v87
	v_pk_fma_f32 v[54:55], v[0:1], v[84:85], v[54:55] op_sel_hi:[1,0,1]
	s_nop 0
	v_pk_fma_f32 v[54:55], v[32:33], v[84:85], v[54:55] op_sel:[0,1,0]
	s_nop 0
	v_pk_fma_f32 v[54:55], v[2:3], v[86:87], v[54:55] op_sel_hi:[1,0,1]
	s_nop 0
	v_pk_fma_f32 v[54:55], v[30:31], v[56:57], v[54:55] op_sel_hi:[1,0,1]
	ds_read_b128 v[76:79], v25 offset:400
	v_pk_fma_f32 v[56:57], v[22:23], v[48:49], v[66:67] neg_lo:[0,0,1] neg_hi:[0,0,1]
	v_pk_fma_f32 v[48:49], v[22:23], v[48:49], v[66:67] op_sel_hi:[1,0,1]
	s_nop 0
	v_mov_b32_e32 v57, v49
	v_pk_add_f32 v[48:49], v[56:57], v[54:55]
	s_nop 0
	v_pk_mul_f32 v[66:67], v[46:47], v[48:49] op_sel:[0,1]
	ds_read_b128 v[80:83], v25 offset:416
	s_waitcnt lgkmcnt(10)
	v_pk_fma_f32 v[62:63], v[12:13], v[88:89], 0 op_sel_hi:[1,0,0]
	s_nop 0
	v_pk_fma_f32 v[54:55], v[44:45], v[88:89], v[62:63] op_sel:[0,1,0]
	s_nop 0
	v_pk_fma_f32 v[54:55], v[14:15], v[90:91], v[54:55] op_sel_hi:[1,0,1]
	v_mov_b32_e32 v56, v91
	v_pk_fma_f32 v[54:55], v[42:43], v[56:57], v[54:55] op_sel_hi:[1,0,1]
	ds_read_b128 v[84:87], v25 offset:432
	s_waitcnt lgkmcnt(10)
	v_pk_fma_f32 v[54:55], v[8:9], v[92:93], v[54:55] op_sel_hi:[1,0,1]
	s_nop 0
	v_pk_fma_f32 v[58:59], v[40:41], v[92:93], v[54:55] op_sel:[0,1,0]
	s_nop 0
	v_pk_fma_f32 v[58:59], v[10:11], v[94:95], v[58:59] op_sel_hi:[1,0,1]
	v_mov_b32_e32 v60, v95
	v_pk_fma_f32 v[58:59], v[38:39], v[60:61], v[58:59] op_sel_hi:[1,0,1]
	s_waitcnt lgkmcnt(9)
	v_pk_fma_f32 v[58:59], v[4:5], v[96:97], v[58:59] op_sel_hi:[1,0,1]
	s_nop 0
	v_pk_fma_f32 v[54:55], v[36:37], v[96:97], v[58:59] op_sel:[0,1,0]
	s_nop 0
	v_pk_fma_f32 v[54:55], v[6:7], v[98:99], v[54:55] op_sel_hi:[1,0,1]
	v_mov_b32_e32 v56, v99
	v_pk_fma_f32 v[54:55], v[34:35], v[56:57], v[54:55] op_sel_hi:[1,0,1]
	ds_read_b128 v[88:91], v25 offset:448
	s_waitcnt lgkmcnt(9)
	v_mov_b32_e32 v56, v103
	v_pk_fma_f32 v[54:55], v[0:1], v[100:101], v[54:55] op_sel_hi:[1,0,1]
	s_nop 0
	v_pk_fma_f32 v[54:55], v[32:33], v[100:101], v[54:55] op_sel:[0,1,0]
	s_nop 0
	v_pk_fma_f32 v[54:55], v[2:3], v[102:103], v[54:55] op_sel_hi:[1,0,1]
	s_nop 0
	v_pk_fma_f32 v[54:55], v[30:31], v[56:57], v[54:55] op_sel_hi:[1,0,1]
	ds_read_b128 v[92:95], v25 offset:464
	v_pk_fma_f32 v[56:57], v[22:23], v[48:49], v[66:67] neg_lo:[0,0,1] neg_hi:[0,0,1]
	v_pk_fma_f32 v[48:49], v[22:23], v[48:49], v[66:67] op_sel_hi:[1,0,1]
	s_nop 0
	v_mov_b32_e32 v57, v49
	v_pk_add_f32 v[48:49], v[56:57], v[54:55]
	s_nop 0
	v_pk_mul_f32 v[66:67], v[46:47], v[48:49] op_sel:[0,1]
	ds_read_b128 v[96:99], v25 offset:480
	s_waitcnt lgkmcnt(10)
	v_pk_fma_f32 v[62:63], v[12:13], v[104:105], 0 op_sel_hi:[1,0,0]
	s_nop 0
	v_pk_fma_f32 v[54:55], v[44:45], v[104:105], v[62:63] op_sel:[0,1,0]
	s_nop 0
	v_pk_fma_f32 v[54:55], v[14:15], v[106:107], v[54:55] op_sel_hi:[1,0,1]
	v_mov_b32_e32 v56, v107
	v_pk_fma_f32 v[54:55], v[42:43], v[56:57], v[54:55] op_sel_hi:[1,0,1]
	ds_read_b128 v[100:103], v25 offset:496
	s_waitcnt lgkmcnt(10)
; #define LAS __attribute__((address_space(3)))
; DI float lo16(unsigned u) { return __uint_as_float(u << 16); }
; DI float hi16(unsigned u) { return __uint_as_float(u & 0xffff0000u); }
; DI float gelu_tanh(float x) { float u = 0.7978845608028654f * (x + 0.044715f * x * x * x); float e = __expf(2.f * u); float th = 1.f - 2.f / (e + 1.f); return 0.5f * x * (1.f + th); }
; DI void lds_wait() { asm volatile("s_waitcnt lgkmcnt(0)" ::: "memory"); }
; template <bool PASSB>
; DI void s5_pass(const int tid, LAS unsigned char* lds, const P& p, int G, int c0) {
;     ...
;         for (int tile = 0; tile < 16; ++tile) {
;             if (lane < 32) { const int tk = lane >> 1, hf = lane & 1;
;                 const u32x4 raw = *(const u32x4*)(us5 + (tokbase + tile * 16 + tk) * 256 + g * 16 + hf * 8);
;                 LAS float* d = ubuf + tk * 16 + hf * 8;
;                 *(LAS f32x4*)d = (f32x4){lo16(raw.x), hi16(raw.x), lo16(raw.y), hi16(raw.y)}; *(LAS f32x4*)(d + 4) = (f32x4){lo16(raw.z), hi16(raw.z), lo16(raw.w), hi16(raw.w)}; }
;             lds_wait();
; #pragma unroll 8
;             for (int t = 0; t < 16; ++t) {
;                 float bur = 0.f, bui = 0.f;
; #pragma unroll
;                 for (int k = 0; k < 4; ++k) { const f32x4 u = *(const LAS f32x4*)(ubuf + t * 16 + k * 4);
; #pragma unroll
;                     for (int e = 0; e < 4; ++e) { bur += bre[4 * k + e] * u[e]; bui += bim[4 * k + e] * u[e]; } }
;                 const float nr = are * hre - aim * him + bur, ni = are * him + aim * hre + bui; hre = nr; him = ni;
;                 if (PASSB) { hbuf[t * 136 + lane] = f2bf(hre); hbuf[t * 136 + 64 + lane] = f2bf(-him); }
;             }
;             if (PASSB) {
;                 lds_wait();
;                 f32x4 acc = (f32x4){0.f, 0.f, 0.f, 0.f};
; #pragma unroll
;                 for (int ks = 0; ks < 4; ++ks) { const bf16x8 a = *(const LAS bf16x8*)(hbuf + fr * 136 + ks * 32 + fq * 8); acc = mfma16(a, cf[ks], acc); }
; #pragma unroll
;                 for (int j = 0; j < 4; ++j) { const int tk = fq * 4 + j; const float y = acc[j] + dsk * ubuf[tk * 16 + fr];
;                     zs5[(tokbase + tile * 16 + tk) * 256 + g * 16 + fr] = f2bf(gelu_tanh(y)); }
;             }
;             lds_wait();
;         }
;         if (!PASSB) { float* he = hend + (((size_t)(b * 16 + g) * 8 + seg) * 64 + lane) * 2; he[0] = hre; he[1] = him; }
	v_pk_fma_f32 v[54:55], v[8:9], v[108:109], v[54:55] op_sel_hi:[1,0,1]
	s_nop 0
	v_pk_fma_f32 v[58:59], v[40:41], v[108:109], v[54:55] op_sel:[0,1,0]
	s_nop 0
	v_pk_fma_f32 v[58:59], v[10:11], v[110:111], v[58:59] op_sel_hi:[1,0,1]
	v_mov_b32_e32 v60, v111
	v_pk_fma_f32 v[58:59], v[38:39], v[60:61], v[58:59] op_sel_hi:[1,0,1]
	s_waitcnt lgkmcnt(9)
	v_pk_fma_f32 v[58:59], v[4:5], v[112:113], v[58:59] op_sel_hi:[1,0,1]
	s_nop 0
	v_pk_fma_f32 v[54:55], v[36:37], v[112:113], v[58:59] op_sel:[0,1,0]
	s_nop 0
	v_pk_fma_f32 v[54:55], v[6:7], v[114:115], v[54:55] op_sel_hi:[1,0,1]
	v_mov_b32_e32 v56, v115
	v_pk_fma_f32 v[54:55], v[34:35], v[56:57], v[54:55] op_sel_hi:[1,0,1]
	s_waitcnt lgkmcnt(8)
	v_mov_b32_e32 v56, v119
	v_pk_fma_f32 v[54:55], v[0:1], v[116:117], v[54:55] op_sel_hi:[1,0,1]
	s_nop 0
	v_pk_fma_f32 v[54:55], v[32:33], v[116:117], v[54:55] op_sel:[0,1,0]
	s_nop 0
	v_pk_fma_f32 v[54:55], v[2:3], v[118:119], v[54:55] op_sel_hi:[1,0,1]
	s_nop 0
	v_pk_fma_f32 v[54:55], v[30:31], v[56:57], v[54:55] op_sel_hi:[1,0,1]
	v_pk_fma_f32 v[56:57], v[22:23], v[48:49], v[66:67] neg_lo:[0,0,1] neg_hi:[0,0,1]
	v_pk_fma_f32 v[48:49], v[22:23], v[48:49], v[66:67] op_sel_hi:[1,0,1]
	s_nop 0
	v_mov_b32_e32 v57, v49
	v_pk_add_f32 v[48:49], v[56:57], v[54:55]
	s_nop 0
	v_pk_mul_f32 v[66:67], v[46:47], v[48:49] op_sel:[0,1]
	s_waitcnt lgkmcnt(7)
	v_pk_fma_f32 v[62:63], v[12:13], v[72:73], 0 op_sel_hi:[1,0,0]
	s_nop 0
	v_pk_fma_f32 v[54:55], v[44:45], v[72:73], v[62:63] op_sel:[0,1,0]
	s_nop 0
	v_pk_fma_f32 v[54:55], v[14:15], v[74:75], v[54:55] op_sel_hi:[1,0,1]
	v_mov_b32_e32 v56, v75
	v_pk_fma_f32 v[54:55], v[42:43], v[56:57], v[54:55] op_sel_hi:[1,0,1]
	s_waitcnt lgkmcnt(6)
	v_pk_fma_f32 v[54:55], v[8:9], v[76:77], v[54:55] op_sel_hi:[1,0,1]
	s_nop 0
	v_pk_fma_f32 v[58:59], v[40:41], v[76:77], v[54:55] op_sel:[0,1,0]
	s_nop 0
	v_pk_fma_f32 v[58:59], v[10:11], v[78:79], v[58:59] op_sel_hi:[1,0,1]
	v_mov_b32_e32 v60, v79
	v_pk_fma_f32 v[58:59], v[38:39], v[60:61], v[58:59] op_sel_hi:[1,0,1]
	s_waitcnt lgkmcnt(5)
	v_pk_fma_f32 v[58:59], v[4:5], v[80:81], v[58:59] op_sel_hi:[1,0,1]
	s_nop 0
	v_pk_fma_f32 v[54:55], v[36:37], v[80:81], v[58:59] op_sel:[0,1,0]
	s_nop 0
	v_pk_fma_f32 v[54:55], v[6:7], v[82:83], v[54:55] op_sel_hi:[1,0,1]
	v_mov_b32_e32 v56, v83
	v_pk_fma_f32 v[54:55], v[34:35], v[56:57], v[54:55] op_sel_hi:[1,0,1]
	s_waitcnt lgkmcnt(4)
	v_mov_b32_e32 v56, v87
	v_pk_fma_f32 v[54:55], v[0:1], v[84:85], v[54:55] op_sel_hi:[1,0,1]
	s_nop 0
	v_pk_fma_f32 v[54:55], v[32:33], v[84:85], v[54:55] op_sel:[0,1,0]
	s_nop 0
	v_pk_fma_f32 v[54:55], v[2:3], v[86:87], v[54:55] op_sel_hi:[1,0,1]
	s_nop 0
	v_pk_fma_f32 v[54:55], v[30:31], v[56:57], v[54:55] op_sel_hi:[1,0,1]
	v_pk_fma_f32 v[56:57], v[22:23], v[48:49], v[66:67] neg_lo:[0,0,1] neg_hi:[0,0,1]
	v_pk_fma_f32 v[48:49], v[22:23], v[48:49], v[66:67] op_sel_hi:[1,0,1]
	s_nop 0
	v_mov_b32_e32 v57, v49
	v_pk_add_f32 v[48:49], v[56:57], v[54:55]
	s_nop 0
	v_pk_mul_f32 v[66:67], v[46:47], v[48:49] op_sel:[0,1]
	s_waitcnt lgkmcnt(3)
	v_pk_fma_f32 v[62:63], v[12:13], v[88:89], 0 op_sel_hi:[1,0,0]
	s_nop 0
	v_pk_fma_f32 v[54:55], v[44:45], v[88:89], v[62:63] op_sel:[0,1,0]
	s_nop 0
	v_pk_fma_f32 v[54:55], v[14:15], v[90:91], v[54:55] op_sel_hi:[1,0,1]
	v_mov_b32_e32 v56, v91
	v_pk_fma_f32 v[54:55], v[42:43], v[56:57], v[54:55] op_sel_hi:[1,0,1]
	s_waitcnt lgkmcnt(2)
	v_pk_fma_f32 v[54:55], v[8:9], v[92:93], v[54:55] op_sel_hi:[1,0,1]
	s_nop 0
	v_pk_fma_f32 v[58:59], v[40:41], v[92:93], v[54:55] op_sel:[0,1,0]
	s_nop 0
	v_pk_fma_f32 v[58:59], v[10:11], v[94:95], v[58:59] op_sel_hi:[1,0,1]
	v_mov_b32_e32 v60, v95
	v_pk_fma_f32 v[58:59], v[38:39], v[60:61], v[58:59] op_sel_hi:[1,0,1]
	s_waitcnt lgkmcnt(1)
	v_pk_fma_f32 v[58:59], v[4:5], v[96:97], v[58:59] op_sel_hi:[1,0,1]
	s_nop 0
	v_pk_fma_f32 v[54:55], v[36:37], v[96:97], v[58:59] op_sel:[0,1,0]
	s_nop 0
	v_pk_fma_f32 v[54:55], v[6:7], v[98:99], v[54:55] op_sel_hi:[1,0,1]
	v_mov_b32_e32 v56, v99
	v_pk_fma_f32 v[54:55], v[34:35], v[56:57], v[54:55] op_sel_hi:[1,0,1]
	s_waitcnt lgkmcnt(0)
	v_mov_b32_e32 v56, v103
	v_pk_fma_f32 v[54:55], v[0:1], v[100:101], v[54:55] op_sel_hi:[1,0,1]
	s_nop 0
	v_pk_fma_f32 v[54:55], v[32:33], v[100:101], v[54:55] op_sel:[0,1,0]
	s_nop 0
	v_pk_fma_f32 v[54:55], v[2:3], v[102:103], v[54:55] op_sel_hi:[1,0,1]
	s_nop 0
	v_pk_fma_f32 v[54:55], v[30:31], v[56:57], v[54:55] op_sel_hi:[1,0,1]
	v_pk_fma_f32 v[56:57], v[22:23], v[48:49], v[66:67] neg_lo:[0,0,1] neg_hi:[0,0,1]
	v_pk_fma_f32 v[48:49], v[22:23], v[48:49], v[66:67] op_sel_hi:[1,0,1]
	s_nop 0
	v_mov_b32_e32 v57, v49
	v_pk_add_f32 v[48:49], v[56:57], v[54:55]
	s_cbranch_scc1 .LBB0_588
	s_waitcnt lgkmcnt(0)
	s_add_i32 s6, s6, 1
	s_cmp_eq_u32 s6, 16
	s_cbranch_scc0 .LBB0_585
	v_lshl_add_u32 v0, v24, 4, s5
	v_ashrrev_i32_e32 v1, 31, v0
	v_readlane_b32 s0, v253, 16
	v_lshlrev_b64 v[0:1], 12, v[0:1]
	s_add_i32 s4, s4, s0
	v_lshl_add_u64 v[0:1], v[20:21], 0, v[0:1]
	s_cmpk_gt_i32 s4, 0x1ff
	v_readlane_b32 s1, v253, 17
	global_store_dwordx2 v[0:1], v[48:49], off
	s_cbranch_scc0 .LBB0_584
